# plus Q-projection epilogue prefetch of statistics / rotary-table lines
# baseline (speedup 1.0000x reference)
; DI unsigned pk2(float lo, float hi) { const f32x2 v = {lo, hi}; const hwbf16x2 b = __builtin_convertvector(v, hwbf16x2); return __builtin_bit_cast(unsigned, b); }
;     DI void operator()(const f32x4 (&acc)[2][2][4][2], const pg8::Unit& u, int wr, int wc, int fr, int fq) const {
;         asm volatile("" : "+v"(fr), "+v"(fq));
;         const int row0 = u.pm * 256 + wr * 64 + fr, col0 = wc * 32 + 8 * fq;
; #pragma unroll
;         for (int ai = 0; ai < 2; ++ai)
; #pragma unroll
;             for (int m = 0; m < 4; ++m) {
;                 const int row = row0 + ai * 128 + m * 16; const f32x4 p = *(const f32x4*)(SSQ + (size_t)row * 4);
;                 const float rs = QSCALE * __builtin_amdgcn_rsqf(((p[0] + p[1]) + (p[2] + p[3])) * (1.0f / 256.0f) + EPS);
; #pragma unroll
;                 for (int bj = 0; bj < 2; ++bj) { f32x4 v0 = acc[ai][bj][m][0] * rs, v1 = acc[ai][bj][m][1] * rs;
;                     if ((wc & 1) && fq < 2) rope4(v0, v1, ROPE16 + (size_t)row * 16, fq);
;                     u32x4 w; w.x = pk2(v0[0], v0[1]); w.y = pk2(v0[2], v0[3]); w.z = pk2(v1[0], v1[1]); w.w = pk2(v1[2], v1[3]);
;                     *(u32x4*)(Q + (size_t)row * 256 + bj * 128 + col0) = w; }
.LBB0_1274:
	s_lshl_b32 s2, s15, 8
	v_readlane_b32 s3, v254, 58
	v_mov_b32_e32 v136, v146
	v_mov_b32_e32 v144, v147
	s_add_i32 s2, s2, s3
	s_nop 0
	v_add_u32_e32 v138, s2, v136
	v_ashrrev_i32_e32 v139, 31, v138
	v_lshl_add_u64 v[136:137], v[138:139], 4, s[36:37]
	global_load_dwordx4 v[220:223], v[136:137], off offset:256
	global_load_dwordx4 v[224:227], v[136:137], off offset:512
	global_load_dwordx4 v[228:231], v[136:137], off offset:768
	global_load_dwordx4 v[232:235], v[136:137], off offset:2048
	global_load_dwordx4 v[236:239], v[136:137], off offset:2304
	global_load_dwordx4 v[240:243], v[136:137], off offset:2560
	global_load_dwordx4 v[244:247], v[136:137], off offset:2816
	global_load_dwordx4 v[140:143], v[136:137], off
	v_lshlrev_b32_e32 v136, 3, v144
	v_cmp_gt_i32_e32 vcc, 2, v144
	v_readlane_b32 s2, v255, 5
	v_readlane_b32 s3, v255, 6
	s_and_b64 s[18:19], s[2:3], vcc
	s_waitcnt vmcnt(0)
	v_mov_b32_e32 v144, v141
	v_mov_b32_e32 v145, v142
	v_mov_b32_e32 v141, v143
	v_pk_add_f32 v[140:141], v[144:145], v[140:141]
	s_nop 0
	v_add_f32_e32 v137, v140, v141
	v_fmamk_f32 v137, v137, 0x3b800000, v202
	v_rsq_f32_e32 v142, v137
	v_lshlrev_b64 v[140:141], 6, v[138:139]
	v_ashrrev_i32_e32 v137, 31, v136
	v_lshl_add_u64 v[150:151], s[38:39], 0, v[140:141]
	v_mul_f32_e32 v140, 0x3e553b94, v142
	v_pk_mul_f32 v[144:145], v[128:129], v[140:141] op_sel_hi:[1,0]
	v_pk_mul_f32 v[142:143], v[126:127], v[140:141] op_sel_hi:[1,0]
	v_pk_mul_f32 v[126:127], v[124:125], v[140:141] op_sel_hi:[1,0]
	v_pk_mul_f32 v[128:129], v[122:123], v[140:141] op_sel_hi:[1,0]
	v_lshl_add_u64 v[124:125], v[136:137], 2, v[150:151]
	s_and_saveexec_b64 s[2:3], s[18:19]
	s_cbranch_execz .LBB0_1276
	global_load_dwordx4 v[164:167], v[124:125], off offset:1024
	global_load_dwordx4 v[164:167], v[124:125], off offset:2048
	global_load_dwordx4 v[164:167], v[124:125], off offset:3072
	s_mov_b64 s[34:35], 0x2000
	v_lshl_add_u64 v[168:169], v[124:125], 0, s[34:35]
	global_load_dwordx4 v[172:175], v[168:169], off
	global_load_dwordx4 v[172:175], v[168:169], off offset:1024
	global_load_dwordx4 v[172:175], v[168:169], off offset:2048
	global_load_dwordx4 v[172:175], v[168:169], off offset:3072
	global_load_dwordx4 v[150:153], v[124:125], off
	global_load_dwordx4 v[154:157], v[124:125], off offset:16
	s_waitcnt vmcnt(1)
	v_mov_b32_e32 v122, v150
	v_mov_b32_e32 v123, v152
	v_mov_b32_e32 v152, v151
	s_waitcnt vmcnt(0)
	v_mul_f32_e32 v150, v144, v154
	v_mul_f32_e32 v158, v126, v155
	v_mul_f32_e32 v160, v144, v155
	v_mul_f32_e32 v154, v126, v154
	v_mov_b32_e32 v126, v145
	v_mov_b32_e32 v144, v127
	v_pk_mul_f32 v[162:163], v[128:129], v[152:153]
	v_pk_mul_f32 v[126:127], v[126:127], v[156:157]
	v_pk_mul_f32 v[144:145], v[144:145], v[156:157]
	v_pk_mul_f32 v[128:129], v[128:129], v[122:123]
	v_mov_b32_e32 v151, v126
	v_mov_b32_e32 v159, v127
	v_pk_fma_f32 v[122:123], v[142:143], v[122:123], v[162:163] neg_lo:[0,0,1] neg_hi:[0,0,1]
	v_mov_b32_e32 v161, v145
	v_mov_b32_e32 v155, v144
	v_pk_fma_f32 v[128:129], v[142:143], v[152:153], v[128:129]
	v_pk_add_f32 v[144:145], v[150:151], v[158:159] neg_lo:[0,1] neg_hi:[0,1]
	v_pk_add_f32 v[126:127], v[160:161], v[154:155]
	v_mov_b32_e32 v142, v122
	v_mov_b32_e32 v143, v123
